# stack: P0 startup hold + attention next-unit Q prefetch + DPP wave sums in the RMSNorm pass + pre-pass k-row loads requested with the gate rows
# speedup vs baseline: 1.0050x; 1.0034x over previous
.LBB0_142:
	s_or_b64 exec, exec, s[6:7]
	s_waitcnt vmcnt(7)
	v_pk_mul_f32 v[82:83], v[8:9], v[8:9]
	v_pk_mul_f32 v[84:85], v[6:7], v[6:7]
	s_waitcnt vmcnt(6)
	v_pk_mul_f32 v[78:79], v[16:17], v[16:17]
	v_pk_mul_f32 v[80:81], v[14:15], v[14:15]
	v_pk_mov_b32 v[86:87], v[84:85], v[82:83] op_sel:[1,0]
	v_mov_b32_e32 v85, v83
	v_pk_add_f32 v[82:83], v[86:87], v[84:85]
	v_pk_mov_b32 v[84:85], v[80:81], v[78:79] op_sel:[1,0]
	v_mov_b32_e32 v81, v79
	v_pk_add_f32 v[78:79], v[84:85], v[80:81]
	v_pk_add_f32 v[82:83], v[82:83], v[82:83] op_sel_hi:[0,1]
	v_pk_add_f32 v[78:79], v[78:79], v[78:79] op_sel_hi:[0,1]
	s_waitcnt vmcnt(3)
	v_mul_f32_e32 v78, v26, v26
	v_pk_fma_f32 v[80:81], v[26:27], v[26:27], v[78:79] op_sel_hi:[1,1,0]
	v_mul_f32_e32 v78, v28, v28
	v_pk_fma_f32 v[84:85], v[28:29], v[28:29], v[78:79] op_sel_hi:[1,1,0]
	s_waitcnt vmcnt(2)
	v_mul_f32_e32 v80, v30, v30
	v_mul_f32_e32 v84, v31, v31
	v_mul_f32_e32 v82, v32, v32
	v_mul_f32_e32 v78, v33, v33
	v_pk_add_f32 v[80:81], v[80:81], v[84:85]
	v_pk_add_f32 v[78:79], v[82:83], v[78:79]
	v_pk_mul_f32 v[82:83], v[4:5], v[4:5]
	v_pk_add_f32 v[78:79], v[80:81], v[78:79]
	v_pk_mul_f32 v[84:85], v[2:3], v[2:3]
	v_add_f32_e32 v86, v78, v79
	v_pk_mul_f32 v[78:79], v[12:13], v[12:13]
	v_pk_mul_f32 v[80:81], v[10:11], v[10:11]
	s_lshl_b32 s0, s0, 5
	s_or_b32 s0, s0, s1
	v_add_f32_dpp v88, v86, v86 quad_perm:[1,0,3,2] row_mask:0xf bank_mask:0xf
	v_pk_mov_b32 v[86:87], v[84:85], v[82:83] op_sel:[1,0]
	v_mov_b32_e32 v85, v83
	v_pk_add_f32 v[82:83], v[86:87], v[84:85]
	v_pk_mov_b32 v[84:85], v[80:81], v[78:79] op_sel:[1,0]
	v_pk_add_f32 v[82:83], v[82:83], v[82:83] op_sel_hi:[0,1]
	v_add_f32_dpp v82, v88, v88 quad_perm:[2,3,0,1] row_mask:0xf bank_mask:0xf
	v_mov_b32_e32 v81, v79
	v_pk_add_f32 v[78:79], v[84:85], v[80:81]
	s_or_b32 s12, s10, s0
	v_pk_add_f32 v[78:79], v[78:79], v[78:79] op_sel_hi:[0,1]
	v_add_f32_dpp v82, v82, v82 row_half_mirror row_mask:0xf bank_mask:0xf
	s_waitcnt vmcnt(1)
	v_mul_f32_e32 v78, v18, v18
	v_pk_fma_f32 v[80:81], v[18:19], v[18:19], v[78:79] op_sel_hi:[1,1,0]
	v_mul_f32_e32 v78, v20, v20
	v_pk_fma_f32 v[84:85], v[20:21], v[20:21], v[78:79] op_sel_hi:[1,1,0]
	v_add_f32_dpp v86, v82, v82 row_mirror row_mask:0xf bank_mask:0xf
	s_waitcnt vmcnt(0)
	v_mul_f32_e32 v80, v22, v22
	v_mul_f32_e32 v84, v23, v23
	v_mul_f32_e32 v82, v24, v24
	v_mul_f32_e32 v78, v25, v25
	v_pk_add_f32 v[80:81], v[80:81], v[84:85]
	v_pk_add_f32 v[78:79], v[82:83], v[78:79]
	v_mov_b32_e32 v87, v86
	v_pk_add_f32 v[78:79], v[80:81], v[78:79]
	s_mov_b32 s13, s11
	v_add_f32_e32 v78, v78, v79
	s_nop 0
	v_permlane16_swap_b32_e32 v86, v87
	v_add_f32_e32 v86, v86, v87
	v_mov_b32_e32 v87, v86
	v_readfirstlane_b32 s0, v77
	v_add_f32_dpp v78, v78, v78 quad_perm:[1,0,3,2] row_mask:0xf bank_mask:0xf
	s_nop 0
	v_permlane32_swap_b32_e32 v86, v87
	v_add_f32_e32 v79, v86, v87
	v_fmamk_f32 v79, v79, 0x3a800000, v75
	v_mul_f32_e32 v80, 0x4f800000, v79
	v_cmp_gt_f32_e32 vcc, s14, v79
	v_add_f32_dpp v78, v78, v78 quad_perm:[2,3,0,1] row_mask:0xf bank_mask:0xf
	v_cndmask_b32_e32 v79, v79, v80, vcc
	v_sqrt_f32_e32 v80, v79
	s_nop 0
	v_add_f32_dpp v78, v78, v78 row_half_mirror row_mask:0xf bank_mask:0xf
	v_add_u32_e32 v82, -1, v80
	v_fma_f32 v83, -v82, v80, v79
	v_cmp_ge_f32_e64 s[6:7], 0, v83
	v_add_u32_e32 v83, 1, v80
	v_add_f32_dpp v78, v78, v78 row_mirror row_mask:0xf bank_mask:0xf
	v_mov_b32_e32 v81, v78
	v_cndmask_b32_e64 v82, v80, v82, s[6:7]
	v_fma_f32 v80, -v83, v80, v79
	v_cmp_lt_f32_e64 s[6:7], 0, v80
	v_permlane16_swap_b32_e32 v78, v81
	v_add_f32_e32 v78, v78, v81
	v_cndmask_b32_e64 v80, v82, v83, s[6:7]
	v_mul_f32_e32 v82, 0x37800000, v80
	v_mov_b32_e32 v81, v78
	v_cndmask_b32_e32 v80, v80, v82, vcc
	v_cmp_class_f32_e32 vcc, v79, v76
	s_nop 0
	v_permlane32_swap_b32_e32 v78, v81
	v_add_f32_e32 v78, v78, v81
	v_cndmask_b32_e32 v79, v80, v79, vcc
	v_div_scale_f32 v80, s[6:7], v79, v79, 1.0
	v_rcp_f32_e32 v82, v80
	v_fmamk_f32 v78, v78, 0x3a800000, v75
	v_mul_f32_e32 v81, 0x4f800000, v78
	v_cmp_gt_f32_e64 s[6:7], s14, v78
	v_fma_f32 v83, -v80, v82, 1.0
	v_fmac_f32_e32 v82, v83, v82
	v_cndmask_b32_e64 v78, v78, v81, s[6:7]
	v_div_scale_f32 v83, vcc, 1.0, v79, 1.0
	v_sqrt_f32_e32 v81, v78
	v_mul_f32_e32 v84, v83, v82
	v_fma_f32 v85, -v80, v84, v83
	v_fmac_f32_e32 v84, v85, v82
	v_fma_f32 v80, -v80, v84, v83
	v_add_u32_e32 v83, -1, v81
	v_fma_f32 v85, -v83, v81, v78
	v_cmp_ge_f32_e64 s[8:9], 0, v85
	v_add_u32_e32 v85, 1, v81
	s_nop 0
	v_cndmask_b32_e64 v83, v81, v83, s[8:9]
	v_fma_f32 v81, -v85, v81, v78
	v_cmp_lt_f32_e64 s[8:9], 0, v81
	s_nop 1
	v_cndmask_b32_e64 v81, v83, v85, s[8:9]
	v_mul_f32_e32 v83, 0x37800000, v81
	v_cndmask_b32_e64 v81, v81, v83, s[6:7]
	v_cmp_class_f32_e64 s[6:7], v78, v76
	s_nop 1
	v_cndmask_b32_e64 v81, v81, v78, s[6:7]
	v_div_scale_f32 v83, s[6:7], v81, v81, 1.0
	v_rcp_f32_e32 v85, v83
	v_div_fmas_f32 v78, v80, v82, v84
	v_div_fixup_f32 v78, v78, v79, 1.0
	s_lshl_b64 s[6:7], s[12:13], 11
	v_fma_f32 v79, -v83, v85, 1.0
	v_fmac_f32_e32 v85, v79, v85
	v_div_scale_f32 v79, vcc, 1.0, v81, 1.0
	v_mul_f32_e32 v80, v79, v85
	v_fma_f32 v82, -v83, v80, v79
	v_fmac_f32_e32 v80, v82, v85
	v_fma_f32 v79, -v83, v80, v79
	v_div_fmas_f32 v79, v79, v85, v80
	v_pk_mul_f32 v[84:85], v[6:7], v[78:79] op_sel_hi:[1,0]
	v_div_fixup_f32 v80, v79, v81, 1.0
	v_pk_fma_f32 v[84:85], v[62:63], v[84:85], v[34:35]
	v_pk_mul_f32 v[86:87], v[8:9], v[78:79] op_sel_hi:[1,0]
	v_bfe_u32 v79, v84, 16, 1
	v_pk_mul_f32 v[88:89], v[2:3], v[80:81] op_sel_hi:[1,0]
	v_pk_mul_f32 v[90:91], v[4:5], v[80:81] op_sel_hi:[1,0]
	v_add3_u32 v79, v84, v79, s15
	v_bfe_u32 v81, v85, 16, 1
	v_pk_fma_f32 v[86:87], v[64:65], v[86:87], v[36:37]
	v_lshrrev_b32_e32 v79, 16, v79
	v_add3_u32 v81, v85, v81, s15
	v_and_or_b32 v84, v81, s16, v79
	v_bfe_u32 v79, v86, 16, 1
	v_add3_u32 v79, v86, v79, s15
	v_bfe_u32 v81, v87, 16, 1
	v_pk_fma_f32 v[88:89], v[62:63], v[88:89], v[34:35]
	v_lshrrev_b32_e32 v79, 16, v79
	v_add3_u32 v81, v87, v81, s15
	v_and_or_b32 v85, v81, s16, v79
	v_bfe_u32 v79, v88, 16, 1
	v_add3_u32 v79, v88, v79, s15
	v_bfe_u32 v81, v89, 16, 1
	v_lshl_add_u64 v[82:83], v[66:67], 0, s[6:7]
	v_pk_fma_f32 v[90:91], v[64:65], v[90:91], v[36:37]
	v_lshrrev_b32_e32 v79, 16, v79
	v_add3_u32 v81, v89, v81, s15
	global_store_dwordx2 v[82:83], v[84:85], off sc1
	v_and_or_b32 v84, v81, s16, v79
	v_bfe_u32 v79, v90, 16, 1
	v_add3_u32 v79, v90, v79, s15
	v_bfe_u32 v81, v91, 16, 1
	v_lshrrev_b32_e32 v79, 16, v79
	v_add3_u32 v81, v91, v81, s15
	v_and_or_b32 v85, v81, s16, v79
	global_store_dwordx2 v[82:83], v[84:85], off offset:2048 sc1
	v_pk_mul_f32 v[84:85], v[14:15], v[78:79] op_sel_hi:[1,0]
	v_pk_mul_f32 v[86:87], v[16:17], v[78:79] op_sel_hi:[1,0]
	v_pk_fma_f32 v[84:85], v[58:59], v[84:85], v[38:39]
	v_pk_mul_f32 v[88:89], v[10:11], v[80:81] op_sel_hi:[1,0]
	v_bfe_u32 v79, v84, 16, 1
	v_pk_mul_f32 v[90:91], v[12:13], v[80:81] op_sel_hi:[1,0]
	v_add3_u32 v79, v84, v79, s15
	v_bfe_u32 v81, v85, 16, 1
	v_pk_fma_f32 v[86:87], v[60:61], v[86:87], v[40:41]
	v_lshrrev_b32_e32 v79, 16, v79
	v_add3_u32 v81, v85, v81, s15
	v_and_or_b32 v84, v81, s16, v79
	v_bfe_u32 v79, v86, 16, 1
	v_add3_u32 v79, v86, v79, s15
	v_bfe_u32 v81, v87, 16, 1
	v_pk_fma_f32 v[88:89], v[58:59], v[88:89], v[38:39]
	v_lshrrev_b32_e32 v79, 16, v79
	v_add3_u32 v81, v87, v81, s15
	v_and_or_b32 v85, v81, s16, v79
	v_bfe_u32 v79, v88, 16, 1
	v_add3_u32 v79, v88, v79, s15
	v_bfe_u32 v81, v89, 16, 1
	v_pk_fma_f32 v[90:91], v[60:61], v[90:91], v[40:41]
	v_lshrrev_b32_e32 v79, 16, v79
	v_add3_u32 v81, v89, v81, s15
	global_store_dwordx2 v[82:83], v[84:85], off offset:512 sc1
	v_and_or_b32 v84, v81, s16, v79
	v_bfe_u32 v79, v90, 16, 1
	v_add3_u32 v79, v90, v79, s15
	v_bfe_u32 v81, v91, 16, 1
	v_lshrrev_b32_e32 v79, 16, v79
	v_add3_u32 v81, v91, v81, s15
	v_and_or_b32 v85, v81, s16, v79
	global_store_dwordx2 v[82:83], v[84:85], off offset:2560 sc1
	v_pk_mul_f32 v[84:85], v[26:27], v[78:79] op_sel_hi:[1,0]
	v_pk_mul_f32 v[86:87], v[28:29], v[78:79] op_sel_hi:[1,0]
	v_pk_fma_f32 v[84:85], v[54:55], v[84:85], v[42:43]
	v_pk_mul_f32 v[88:89], v[18:19], v[80:81] op_sel_hi:[1,0]
	v_bfe_u32 v79, v84, 16, 1
	v_pk_mul_f32 v[90:91], v[20:21], v[80:81] op_sel_hi:[1,0]
	v_add3_u32 v79, v84, v79, s15
	v_bfe_u32 v81, v85, 16, 1
	v_pk_fma_f32 v[86:87], v[56:57], v[86:87], v[44:45]
	v_lshrrev_b32_e32 v79, 16, v79
	v_add3_u32 v81, v85, v81, s15
	v_and_or_b32 v84, v81, s16, v79
	v_bfe_u32 v79, v86, 16, 1
	v_add3_u32 v79, v86, v79, s15
	v_bfe_u32 v81, v87, 16, 1
	v_pk_fma_f32 v[88:89], v[54:55], v[88:89], v[42:43]
	v_lshrrev_b32_e32 v79, 16, v79
	v_add3_u32 v81, v87, v81, s15
	v_and_or_b32 v85, v81, s16, v79
	v_bfe_u32 v79, v88, 16, 1
	v_add3_u32 v79, v88, v79, s15
	v_bfe_u32 v81, v89, 16, 1
	v_pk_fma_f32 v[90:91], v[56:57], v[90:91], v[44:45]
	v_lshrrev_b32_e32 v79, 16, v79
	v_add3_u32 v81, v89, v81, s15
	global_store_dwordx2 v[82:83], v[84:85], off offset:1024 sc1
	v_and_or_b32 v84, v81, s16, v79
	v_bfe_u32 v79, v90, 16, 1
	v_add3_u32 v79, v90, v79, s15
	v_bfe_u32 v81, v91, 16, 1
	v_lshrrev_b32_e32 v79, 16, v79
	v_add3_u32 v81, v91, v81, s15
	v_and_or_b32 v85, v81, s16, v79
	global_store_dwordx2 v[82:83], v[84:85], off offset:3072 sc1
	v_pk_mul_f32 v[84:85], v[30:31], v[78:79] op_sel_hi:[1,0]
	v_pk_mul_f32 v[78:79], v[32:33], v[78:79] op_sel_hi:[1,0]
	s_waitcnt vmcnt(6)
	v_pk_fma_f32 v[84:85], v[50:51], v[84:85], v[46:47]
	v_pk_fma_f32 v[78:79], v[52:53], v[78:79], v[48:49]
	v_bfe_u32 v88, v84, 16, 1
	v_add3_u32 v84, v84, v88, s15
	v_bfe_u32 v88, v85, 16, 1
	v_lshrrev_b32_e32 v84, 16, v84
	v_add3_u32 v85, v85, v88, s15
	v_and_or_b32 v84, v85, s16, v84
	v_bfe_u32 v85, v78, 16, 1
	v_pk_mul_f32 v[86:87], v[22:23], v[80:81] op_sel_hi:[1,0]
	v_add3_u32 v78, v78, v85, s15
	v_bfe_u32 v85, v79, 16, 1
	v_pk_fma_f32 v[86:87], v[50:51], v[86:87], v[46:47]
	v_lshrrev_b32_e32 v78, 16, v78
	v_add3_u32 v79, v79, v85, s15
	v_and_or_b32 v85, v79, s16, v78
	v_bfe_u32 v78, v86, 16, 1
	v_pk_mul_f32 v[80:81], v[24:25], v[80:81] op_sel_hi:[1,0]
	v_add3_u32 v78, v86, v78, s15
	v_bfe_u32 v79, v87, 16, 1
	v_pk_fma_f32 v[80:81], v[52:53], v[80:81], v[48:49]
	v_lshrrev_b32_e32 v78, 16, v78
	v_add3_u32 v79, v87, v79, s15
	v_and_or_b32 v78, v79, s16, v78
	v_bfe_u32 v79, v80, 16, 1
	v_add3_u32 v79, v80, v79, s15
	v_bfe_u32 v80, v81, 16, 1
	s_cmp_gt_u32 s0, 63
	v_lshrrev_b32_e32 v79, 16, v79
	v_add3_u32 v80, v81, v80, s15
	s_cselect_b64 s[6:7], -1, 0
	v_and_or_b32 v79, v80, s16, v79
	s_and_b64 vcc, exec, s[6:7]
	global_store_dwordx2 v[82:83], v[84:85], off offset:1536 sc1
	global_store_dwordx2 v[82:83], v[78:79], off offset:3584 sc1
	s_cbranch_vccnz .LBB0_137
	s_lshl_b32 s8, s0, 5
	s_or_b32 s8, s8, s1
	s_or_b32 s8, s10, s8
	s_mov_b32 s9, s11
	s_lshl_b64 s[8:9], s[8:9], 12
	v_lshl_add_u64 v[78:79], v[68:69], 0, s[8:9]
	v_add_co_u32_e32 v80, vcc, 0x1000, v78
	s_nop 1
	v_addc_co_u32_e32 v81, vcc, 0, v79, vcc
	global_load_dwordx4 v[6:9], v[78:79], off nt
	global_load_dwordx4 v[14:17], v[78:79], off offset:1024 nt
	global_load_dwordx4 v[2:5], v[80:81], off nt
	global_load_dwordx4 v[10:13], v[80:81], off offset:1024 nt
	global_load_dwordx4 v[26:29], v[78:79], off offset:2048 nt
	global_load_dwordx4 v[30:33], v[78:79], off offset:3072 nt
	global_load_dwordx4 v[18:21], v[80:81], off offset:2048 nt
	global_load_dwordx4 v[22:25], v[80:81], off offset:3072 nt
	s_branch .LBB0_137

.LBB0_386:
	s_add_i32 s16, s10, -16
	s_and_b32 s2, s16, 0x7f0
	s_sub_i32 s24, s10, 17
	s_cmp_lg_u32 s2, 0
	s_cselect_b64 s[40:41], -1, 0
	s_cmp_eq_u32 s2, 0
	s_cbranch_scc1 .LBB0_388
	s_ashr_i32 s25, s24, 31
	s_lshl_b64 s[18:19], s[24:25], 8
	v_lshl_add_u64 v[130:131], v[112:113], 0, s[18:19]
	global_load_dword v131, v[130:131], off nt
	s_branch .LBB0_389
.LBB0_388:
	v_mov_b32_e32 v131, 0
.LBB0_389:
	s_ashr_i32 s17, s16, 31
	s_lshl_b64 s[18:19], s[16:17], 8
	v_lshl_add_u64 v[132:133], v[112:113], 0, s[18:19]
	s_add_i32 s18, s10, -15
	s_ashr_i32 s19, s18, 31
	s_lshl_b64 s[26:27], s[18:19], 8
	v_lshl_add_u64 v[134:135], v[112:113], 0, s[26:27]
	s_add_i32 s26, s10, -14
	s_ashr_i32 s27, s26, 31
	s_lshl_b64 s[36:37], s[26:27], 8
	v_lshl_add_u64 v[136:137], v[112:113], 0, s[36:37]
	s_add_i32 s36, s10, -13
	s_ashr_i32 s37, s36, 31
	s_lshl_b64 s[38:39], s[36:37], 8
	v_lshl_add_u64 v[138:139], v[112:113], 0, s[38:39]
	s_add_i32 s38, s10, -12
	s_ashr_i32 s39, s38, 31
	s_lshl_b64 s[42:43], s[38:39], 8
	v_lshl_add_u64 v[140:141], v[112:113], 0, s[42:43]
	s_add_i32 s42, s10, -11
	s_ashr_i32 s43, s42, 31
	s_lshl_b64 s[44:45], s[42:43], 8
	v_lshl_add_u64 v[142:143], v[112:113], 0, s[44:45]
	s_add_i32 s44, s10, -10
	s_ashr_i32 s45, s44, 31
	s_lshl_b64 s[46:47], s[44:45], 8
	v_lshl_add_u64 v[144:145], v[112:113], 0, s[46:47]
	s_add_i32 s46, s10, -9
	s_ashr_i32 s47, s46, 31
	s_lshl_b64 s[48:49], s[46:47], 8
	v_lshl_add_u64 v[152:153], v[112:113], 0, s[48:49]
	s_add_i32 s48, s10, -8
	s_ashr_i32 s49, s48, 31
	s_lshl_b64 s[50:51], s[48:49], 8
	global_load_dword v133, v[132:133], off nt
	s_nop 0
	global_load_dword v134, v[134:135], off nt
	s_nop 0
	global_load_dword v150, v[136:137], off nt
	global_load_dword v149, v[138:139], off nt
	global_load_dword v148, v[140:141], off nt
	global_load_dword v147, v[142:143], off nt
	global_load_dword v146, v[144:145], off nt
	s_nop 0
	global_load_dword v144, v[152:153], off nt
	v_lshl_add_u64 v[136:137], v[112:113], 0, s[50:51]
	s_add_i32 s50, s10, -7
	s_ashr_i32 s51, s50, 31
	s_lshl_b64 s[52:53], s[50:51], 8
	v_lshl_add_u64 v[138:139], v[112:113], 0, s[52:53]
	s_add_i32 s52, s10, -6
	s_ashr_i32 s53, s52, 31
	s_lshl_b64 s[54:55], s[52:53], 8
	v_lshl_add_u64 v[140:141], v[112:113], 0, s[54:55]
	s_add_i32 s54, s10, -5
	s_ashr_i32 s55, s54, 31
	s_lshl_b64 s[56:57], s[54:55], 8
	v_lshl_add_u64 v[152:153], v[112:113], 0, s[56:57]
	s_add_i32 s56, s10, -4
	s_ashr_i32 s57, s56, 31
	s_lshl_b64 s[58:59], s[56:57], 8
	v_lshl_add_u64 v[154:155], v[112:113], 0, s[58:59]
	s_add_i32 s58, s10, -3
	s_ashr_i32 s59, s58, 31
	s_lshl_b64 s[60:61], s[58:59], 8
	v_lshl_add_u64 v[156:157], v[112:113], 0, s[60:61]
	s_add_i32 s60, s10, -2
	s_ashr_i32 s61, s60, 31
	s_lshl_b64 s[62:63], s[60:61], 8
	v_lshl_add_u64 v[158:159], v[112:113], 0, s[62:63]
	s_add_i32 s62, s10, -1
	s_ashr_i32 s63, s62, 31
	s_lshl_b64 s[64:65], s[62:63], 8
	v_lshl_add_u64 v[160:161], v[112:113], 0, s[64:65]
	global_load_dword v145, v[136:137], off nt
	global_load_dword v143, v[138:139], off nt
	global_load_dword v142, v[140:141], off nt
	s_nop 0
	global_load_dword v141, v[152:153], off nt
	global_load_dword v140, v[154:155], off nt
	global_load_dword v139, v[156:157], off nt
	global_load_dword v138, v[158:159], off nt
	global_load_dword v137, v[160:161], off nt
	s_cmpk_lg_i32 s2, 0x7f0
	s_cselect_b64 s[66:67], -1, 0
	s_cmpk_eq_i32 s2, 0x7f0
	v_mov_b32_e32 v136, 0
	s_cbranch_scc1 .LBB0_391
	s_ashr_i32 s11, s10, 31
	s_lshl_b64 s[64:65], s[10:11], 8
	v_lshl_add_u64 v[152:153], v[112:113], 0, s[64:65]
	global_load_dword v136, v[152:153], off nt
.LBB0_391:
	s_andn2_b64 vcc, exec, s[40:41]
	s_cbranch_vccnz .Lpreds_a
	s_ashr_i32 s25, s24, 31
	s_lshl_b64 s[24:25], s[24:25], 10
	v_lshl_add_u64 v[34:35], v[114:115], 0, s[24:25]
	global_load_dwordx4 v[94:97], v[34:35], off nt
	s_branch .Lpreds_b

.Lpreds_c:
	s_waitcnt vmcnt(31)
	v_lshlrev_b32_e32 v132, 16, v133
	v_and_b32_e32 v133, 0xffff0000, v133
	v_lshlrev_b32_e32 v152, 16, v131
	s_waitcnt vmcnt(30)
	v_lshlrev_b32_e32 v130, 16, v134
	v_and_b32_e32 v153, 0xffff0000, v131
	v_and_b32_e32 v131, 0xffff0000, v134
	v_pk_mul_f32 v[134:135], v[108:109], v[132:133]
	s_nop 0
	v_pk_fma_f32 v[134:135], v[106:107], v[152:153], v[134:135]
	s_nop 0
	v_pk_fma_f32 v[134:135], v[110:111], v[130:131], v[134:135]
	s_and_saveexec_b64 s[68:69], s[4:5]
	s_cbranch_execz .LBB0_393
	v_mul_f32_e32 v134, 0x4038aa3b, v134
	v_mul_f32_e32 v135, 0x4038aa3b, v135
	v_exp_f32_e32 v134, v134
	v_exp_f32_e32 v135, v135
	v_add_f32_e32 v134, 1.0, v134
	v_add_f32_e32 v135, 1.0, v135
	v_rcp_f32_e32 v134, v134
	v_rcp_f32_e32 v135, v135
	s_nop 0
	v_pk_fma_f32 v[134:135], v[134:135], -2.0, 1.0 op_sel_hi:[1,0,0]
.LBB0_393:
	s_or_b64 exec, exec, s[68:69]
	v_cvt_pk_bf16_f32 v134, v134, v135
	ds_write_b32 v117, v134
	s_waitcnt vmcnt(29)
	v_lshlrev_b32_e32 v134, 16, v150
	v_and_b32_e32 v135, 0xffff0000, v150
	v_pk_mul_f32 v[150:151], v[108:109], v[130:131]
	s_nop 0
	v_pk_fma_f32 v[132:133], v[106:107], v[132:133], v[150:151]
	s_nop 0
	v_pk_fma_f32 v[132:133], v[110:111], v[134:135], v[132:133]
	s_and_saveexec_b64 s[68:69], s[4:5]
	s_cbranch_execz .LBB0_395
	v_mul_f32_e32 v132, 0x4038aa3b, v132
	v_mul_f32_e32 v133, 0x4038aa3b, v133
	v_exp_f32_e32 v132, v132
	v_exp_f32_e32 v133, v133
	v_add_f32_e32 v132, 1.0, v132
	v_add_f32_e32 v133, 1.0, v133
	v_rcp_f32_e32 v132, v132
	v_rcp_f32_e32 v133, v133
	s_nop 0
	v_pk_fma_f32 v[132:133], v[132:133], -2.0, 1.0 op_sel_hi:[1,0,0]
.LBB0_395:
	s_or_b64 exec, exec, s[68:69]
	v_cvt_pk_bf16_f32 v132, v132, v133
	v_pk_mul_f32 v[150:151], v[108:109], v[134:135]
	ds_write_b32 v117, v132 offset:128
	s_waitcnt vmcnt(28)
	v_lshlrev_b32_e32 v132, 16, v149
	v_and_b32_e32 v133, 0xffff0000, v149
	v_pk_fma_f32 v[130:131], v[106:107], v[130:131], v[150:151]
	s_nop 0
	v_pk_fma_f32 v[130:131], v[110:111], v[132:133], v[130:131]
	s_and_saveexec_b64 s[68:69], s[4:5]
	s_cbranch_execz .LBB0_397
	v_mul_f32_e32 v130, 0x4038aa3b, v130
	v_mul_f32_e32 v131, 0x4038aa3b, v131
	v_exp_f32_e32 v130, v130
	v_exp_f32_e32 v131, v131
	v_add_f32_e32 v130, 1.0, v130
	v_add_f32_e32 v131, 1.0, v131
	v_rcp_f32_e32 v130, v130
	v_rcp_f32_e32 v131, v131
	s_nop 0
	v_pk_fma_f32 v[130:131], v[130:131], -2.0, 1.0 op_sel_hi:[1,0,0]
.LBB0_397:
	s_or_b64 exec, exec, s[68:69]
	v_cvt_pk_bf16_f32 v130, v130, v131
	ds_write_b32 v117, v130 offset:256
	s_waitcnt vmcnt(27)
	v_lshlrev_b32_e32 v130, 16, v148
	v_and_b32_e32 v131, 0xffff0000, v148
	v_pk_mul_f32 v[148:149], v[108:109], v[132:133]
	s_nop 0
	v_pk_fma_f32 v[134:135], v[106:107], v[134:135], v[148:149]
	s_nop 0
	v_pk_fma_f32 v[134:135], v[110:111], v[130:131], v[134:135]
	s_and_saveexec_b64 s[68:69], s[4:5]
	s_cbranch_execz .LBB0_399
	v_mul_f32_e32 v134, 0x4038aa3b, v134
	v_mul_f32_e32 v135, 0x4038aa3b, v135
	v_exp_f32_e32 v134, v134
	v_exp_f32_e32 v135, v135
	v_add_f32_e32 v134, 1.0, v134
	v_add_f32_e32 v135, 1.0, v135
	v_rcp_f32_e32 v134, v134
	v_rcp_f32_e32 v135, v135
	s_nop 0
	v_pk_fma_f32 v[134:135], v[134:135], -2.0, 1.0 op_sel_hi:[1,0,0]
.LBB0_399:
	s_or_b64 exec, exec, s[68:69]
	v_cvt_pk_bf16_f32 v134, v134, v135
	v_pk_mul_f32 v[148:149], v[108:109], v[130:131]
	ds_write_b32 v117, v134 offset:384
	s_waitcnt vmcnt(26)
	v_lshlrev_b32_e32 v134, 16, v147
	v_and_b32_e32 v135, 0xffff0000, v147
	v_pk_fma_f32 v[132:133], v[106:107], v[132:133], v[148:149]
	s_nop 0
	v_pk_fma_f32 v[132:133], v[110:111], v[134:135], v[132:133]
	s_and_saveexec_b64 s[68:69], s[4:5]
	s_cbranch_execz .LBB0_401
	v_mul_f32_e32 v132, 0x4038aa3b, v132
	v_mul_f32_e32 v133, 0x4038aa3b, v133
	v_exp_f32_e32 v132, v132
	v_exp_f32_e32 v133, v133
	v_add_f32_e32 v132, 1.0, v132
	v_add_f32_e32 v133, 1.0, v133
	v_rcp_f32_e32 v132, v132
	v_rcp_f32_e32 v133, v133
	s_nop 0
	v_pk_fma_f32 v[132:133], v[132:133], -2.0, 1.0 op_sel_hi:[1,0,0]
.LBB0_401:
	s_or_b64 exec, exec, s[68:69]
	v_cvt_pk_bf16_f32 v132, v132, v133
	ds_write_b32 v117, v132 offset:512
	s_waitcnt vmcnt(25)
	v_lshlrev_b32_e32 v132, 16, v146
	v_and_b32_e32 v133, 0xffff0000, v146
	v_pk_mul_f32 v[146:147], v[108:109], v[134:135]
	s_nop 0
	v_pk_fma_f32 v[130:131], v[106:107], v[130:131], v[146:147]
	s_nop 0
	v_pk_fma_f32 v[130:131], v[110:111], v[132:133], v[130:131]
	s_and_saveexec_b64 s[68:69], s[4:5]
	s_cbranch_execz .LBB0_403
	v_mul_f32_e32 v130, 0x4038aa3b, v130
	v_mul_f32_e32 v131, 0x4038aa3b, v131
	v_exp_f32_e32 v130, v130
	v_exp_f32_e32 v131, v131
	v_add_f32_e32 v130, 1.0, v130
	v_add_f32_e32 v131, 1.0, v131
	v_rcp_f32_e32 v130, v130
	v_rcp_f32_e32 v131, v131
	s_nop 0
	v_pk_fma_f32 v[130:131], v[130:131], -2.0, 1.0 op_sel_hi:[1,0,0]
.LBB0_403:
	s_or_b64 exec, exec, s[68:69]
	v_cvt_pk_bf16_f32 v130, v130, v131
	v_pk_mul_f32 v[146:147], v[108:109], v[132:133]
	ds_write_b32 v117, v130 offset:640
	s_waitcnt vmcnt(24)
	v_lshlrev_b32_e32 v130, 16, v144
	v_and_b32_e32 v131, 0xffff0000, v144
	v_pk_fma_f32 v[134:135], v[106:107], v[134:135], v[146:147]
	s_nop 0
	v_pk_fma_f32 v[134:135], v[110:111], v[130:131], v[134:135]
	s_and_saveexec_b64 s[68:69], s[4:5]
	s_cbranch_execz .LBB0_405
	v_mul_f32_e32 v134, 0x4038aa3b, v134
	v_mul_f32_e32 v135, 0x4038aa3b, v135
	v_exp_f32_e32 v134, v134
	v_exp_f32_e32 v135, v135
	v_add_f32_e32 v134, 1.0, v134
	v_add_f32_e32 v135, 1.0, v135
	v_rcp_f32_e32 v134, v134
	v_rcp_f32_e32 v135, v135
	s_nop 0
	v_pk_fma_f32 v[134:135], v[134:135], -2.0, 1.0 op_sel_hi:[1,0,0]
.LBB0_405:
	s_or_b64 exec, exec, s[68:69]
	v_cvt_pk_bf16_f32 v134, v134, v135
	ds_write_b32 v117, v134 offset:768
	s_waitcnt vmcnt(23)
	v_lshlrev_b32_e32 v134, 16, v145
	v_and_b32_e32 v135, 0xffff0000, v145
	v_pk_mul_f32 v[144:145], v[108:109], v[130:131]
	s_nop 0
	v_pk_fma_f32 v[132:133], v[106:107], v[132:133], v[144:145]
	s_nop 0
	v_pk_fma_f32 v[132:133], v[110:111], v[134:135], v[132:133]
	s_and_saveexec_b64 s[68:69], s[4:5]
	s_cbranch_execz .LBB0_407
	v_mul_f32_e32 v132, 0x4038aa3b, v132
	v_mul_f32_e32 v133, 0x4038aa3b, v133
	v_exp_f32_e32 v132, v132
	v_exp_f32_e32 v133, v133
	v_add_f32_e32 v132, 1.0, v132
	v_add_f32_e32 v133, 1.0, v133
	v_rcp_f32_e32 v132, v132
	v_rcp_f32_e32 v133, v133
	s_nop 0
	v_pk_fma_f32 v[132:133], v[132:133], -2.0, 1.0 op_sel_hi:[1,0,0]
.LBB0_407:
	s_or_b64 exec, exec, s[68:69]
	v_cvt_pk_bf16_f32 v132, v132, v133
	v_pk_mul_f32 v[144:145], v[108:109], v[134:135]
	ds_write_b32 v117, v132 offset:896
	s_waitcnt vmcnt(22)
	v_lshlrev_b32_e32 v132, 16, v143
	v_and_b32_e32 v133, 0xffff0000, v143
	v_pk_fma_f32 v[130:131], v[106:107], v[130:131], v[144:145]
	s_nop 0
	v_pk_fma_f32 v[130:131], v[110:111], v[132:133], v[130:131]
	s_and_saveexec_b64 s[68:69], s[4:5]
	s_cbranch_execz .LBB0_409
	v_mul_f32_e32 v130, 0x4038aa3b, v130
	v_mul_f32_e32 v131, 0x4038aa3b, v131
	v_exp_f32_e32 v130, v130
	v_exp_f32_e32 v131, v131
	v_add_f32_e32 v130, 1.0, v130
	v_add_f32_e32 v131, 1.0, v131
	v_rcp_f32_e32 v130, v130
	v_rcp_f32_e32 v131, v131
	s_nop 0
	v_pk_fma_f32 v[130:131], v[130:131], -2.0, 1.0 op_sel_hi:[1,0,0]
.LBB0_409:
	s_or_b64 exec, exec, s[68:69]
	v_cvt_pk_bf16_f32 v130, v130, v131
	ds_write_b32 v117, v130 offset:1024
	s_waitcnt vmcnt(21)
	v_lshlrev_b32_e32 v130, 16, v142
	v_and_b32_e32 v131, 0xffff0000, v142
	v_pk_mul_f32 v[142:143], v[108:109], v[132:133]
	s_nop 0
	v_pk_fma_f32 v[134:135], v[106:107], v[134:135], v[142:143]
	s_nop 0
	v_pk_fma_f32 v[134:135], v[110:111], v[130:131], v[134:135]
	s_and_saveexec_b64 s[68:69], s[4:5]
	s_cbranch_execz .LBB0_411
	v_mul_f32_e32 v134, 0x4038aa3b, v134
	v_mul_f32_e32 v135, 0x4038aa3b, v135
	v_exp_f32_e32 v134, v134
	v_exp_f32_e32 v135, v135
	v_add_f32_e32 v134, 1.0, v134
	v_add_f32_e32 v135, 1.0, v135
	v_rcp_f32_e32 v134, v134
	v_rcp_f32_e32 v135, v135
	s_nop 0
	v_pk_fma_f32 v[134:135], v[134:135], -2.0, 1.0 op_sel_hi:[1,0,0]
.LBB0_411:
	s_or_b64 exec, exec, s[68:69]
	v_cvt_pk_bf16_f32 v134, v134, v135
	v_pk_mul_f32 v[142:143], v[108:109], v[130:131]
	ds_write_b32 v117, v134 offset:1152
	s_waitcnt vmcnt(20)
	v_lshlrev_b32_e32 v134, 16, v141
	v_and_b32_e32 v135, 0xffff0000, v141
	v_pk_fma_f32 v[132:133], v[106:107], v[132:133], v[142:143]
	s_nop 0
	v_pk_fma_f32 v[132:133], v[110:111], v[134:135], v[132:133]
	s_and_saveexec_b64 s[68:69], s[4:5]
	s_cbranch_execz .LBB0_413
	v_mul_f32_e32 v132, 0x4038aa3b, v132
	v_mul_f32_e32 v133, 0x4038aa3b, v133
	v_exp_f32_e32 v132, v132
	v_exp_f32_e32 v133, v133
	v_add_f32_e32 v132, 1.0, v132
	v_add_f32_e32 v133, 1.0, v133
	v_rcp_f32_e32 v132, v132
	v_rcp_f32_e32 v133, v133
	s_nop 0
	v_pk_fma_f32 v[132:133], v[132:133], -2.0, 1.0 op_sel_hi:[1,0,0]
.LBB0_413:
	s_or_b64 exec, exec, s[68:69]
	v_cvt_pk_bf16_f32 v132, v132, v133
	ds_write_b32 v117, v132 offset:1280
	s_waitcnt vmcnt(19)
	v_lshlrev_b32_e32 v132, 16, v140
	v_and_b32_e32 v133, 0xffff0000, v140
	v_pk_mul_f32 v[140:141], v[108:109], v[134:135]
	s_nop 0
	v_pk_fma_f32 v[130:131], v[106:107], v[130:131], v[140:141]
	s_nop 0
	v_pk_fma_f32 v[130:131], v[110:111], v[132:133], v[130:131]
	s_and_saveexec_b64 s[68:69], s[4:5]
	s_cbranch_execz .LBB0_415
	v_mul_f32_e32 v130, 0x4038aa3b, v130
	v_mul_f32_e32 v131, 0x4038aa3b, v131
	v_exp_f32_e32 v130, v130
	v_exp_f32_e32 v131, v131
	v_add_f32_e32 v130, 1.0, v130
	v_add_f32_e32 v131, 1.0, v131
	v_rcp_f32_e32 v130, v130
	v_rcp_f32_e32 v131, v131
	s_nop 0
	v_pk_fma_f32 v[130:131], v[130:131], -2.0, 1.0 op_sel_hi:[1,0,0]
.LBB0_415:
	s_or_b64 exec, exec, s[68:69]
	v_cvt_pk_bf16_f32 v130, v130, v131
	v_pk_mul_f32 v[140:141], v[108:109], v[132:133]
	ds_write_b32 v117, v130 offset:1408
	s_waitcnt vmcnt(18)
	v_lshlrev_b32_e32 v130, 16, v139
	v_and_b32_e32 v131, 0xffff0000, v139
	v_pk_fma_f32 v[134:135], v[106:107], v[134:135], v[140:141]
	s_nop 0
	v_pk_fma_f32 v[134:135], v[110:111], v[130:131], v[134:135]
	s_and_saveexec_b64 s[68:69], s[4:5]
	s_cbranch_execz .LBB0_417
	v_mul_f32_e32 v134, 0x4038aa3b, v134
	v_mul_f32_e32 v135, 0x4038aa3b, v135
	v_exp_f32_e32 v134, v134
	v_exp_f32_e32 v135, v135
	v_add_f32_e32 v134, 1.0, v134
	v_add_f32_e32 v135, 1.0, v135
	v_rcp_f32_e32 v134, v134
	v_rcp_f32_e32 v135, v135
	s_nop 0
	v_pk_fma_f32 v[134:135], v[134:135], -2.0, 1.0 op_sel_hi:[1,0,0]
.LBB0_417:
	s_or_b64 exec, exec, s[68:69]
	v_cvt_pk_bf16_f32 v134, v134, v135
	ds_write_b32 v117, v134 offset:1536
	s_waitcnt vmcnt(17)
	v_lshlrev_b32_e32 v134, 16, v138
	v_and_b32_e32 v135, 0xffff0000, v138
	v_pk_mul_f32 v[138:139], v[108:109], v[130:131]
	s_nop 0
	v_pk_fma_f32 v[132:133], v[106:107], v[132:133], v[138:139]
	s_nop 0
	v_pk_fma_f32 v[132:133], v[110:111], v[134:135], v[132:133]
	s_and_saveexec_b64 s[68:69], s[4:5]
	s_cbranch_execz .LBB0_419
	v_mul_f32_e32 v132, 0x4038aa3b, v132
	v_mul_f32_e32 v133, 0x4038aa3b, v133
	v_exp_f32_e32 v132, v132
	v_exp_f32_e32 v133, v133
	v_add_f32_e32 v132, 1.0, v132
	v_add_f32_e32 v133, 1.0, v133
	v_rcp_f32_e32 v132, v132
	v_rcp_f32_e32 v133, v133
	s_nop 0
	v_pk_fma_f32 v[132:133], v[132:133], -2.0, 1.0 op_sel_hi:[1,0,0]
.LBB0_419:
	s_or_b64 exec, exec, s[68:69]
	v_cvt_pk_bf16_f32 v132, v132, v133
	v_pk_mul_f32 v[138:139], v[108:109], v[134:135]
	ds_write_b32 v117, v132 offset:1664
	s_waitcnt vmcnt(16)
	v_lshlrev_b32_e32 v132, 16, v137
	v_and_b32_e32 v133, 0xffff0000, v137
	v_pk_fma_f32 v[130:131], v[106:107], v[130:131], v[138:139]
	s_nop 0
	v_pk_fma_f32 v[130:131], v[110:111], v[132:133], v[130:131]
	s_and_saveexec_b64 s[68:69], s[4:5]
	s_cbranch_execz .LBB0_421
	v_mul_f32_e32 v130, 0x4038aa3b, v130
	v_mul_f32_e32 v131, 0x4038aa3b, v131
	v_exp_f32_e32 v130, v130
	v_exp_f32_e32 v131, v131
	v_add_f32_e32 v130, 1.0, v130
	v_add_f32_e32 v131, 1.0, v131
	v_rcp_f32_e32 v130, v130
	v_rcp_f32_e32 v131, v131
	s_nop 0
	v_pk_fma_f32 v[130:131], v[130:131], -2.0, 1.0 op_sel_hi:[1,0,0]
.LBB0_421:
	s_or_b64 exec, exec, s[68:69]
	v_cvt_pk_bf16_f32 v130, v130, v131
	ds_write_b32 v117, v130 offset:1792
	v_pk_mul_f32 v[130:131], v[108:109], v[132:133]
	v_lshlrev_b32_e32 v132, 16, v136
	v_and_b32_e32 v133, 0xffff0000, v136
	v_pk_fma_f32 v[130:131], v[106:107], v[134:135], v[130:131]
	s_nop 0
	v_pk_fma_f32 v[130:131], v[110:111], v[132:133], v[130:131]
	s_and_saveexec_b64 s[68:69], s[4:5]
	s_cbranch_execz .LBB0_423
	v_mul_f32_e32 v130, 0x4038aa3b, v130
	v_mul_f32_e32 v131, 0x4038aa3b, v131
	v_exp_f32_e32 v130, v130
	v_exp_f32_e32 v131, v131
	v_add_f32_e32 v130, 1.0, v130
	v_add_f32_e32 v131, 1.0, v131
	v_rcp_f32_e32 v130, v130
	v_rcp_f32_e32 v131, v131
	s_nop 0
	v_pk_fma_f32 v[130:131], v[130:131], -2.0, 1.0 op_sel_hi:[1,0,0]
.LBB0_423:
	s_or_b64 exec, exec, s[68:69]
	v_cvt_pk_bf16_f32 v130, v130, v131
	ds_write_b32 v117, v130 offset:1920
	v_add_u32_e32 v120, s28, v116
	ds_read_b128 v[130:133], v120
	ds_read_b128 v[134:137], v120 offset:1024
	v_add_u32_e32 v142, s31, v116
	v_add_u32_e32 v143, 0x1a800000, v142
	ds_read_b128 v[138:141], v120 offset:2048
	s_waitcnt lgkmcnt(2)
	buffer_store_dwordx4 v[130:133], v143, s[12:15], 0 offen sc1
	s_waitcnt lgkmcnt(1)
	buffer_store_dwordx4 v[134:137], v143, s[12:15], 0 offen offset:1024 sc1
	ds_read_b128 v[130:133], v118 offset:3072
	s_nop 0
	v_add_u32_e32 v134, 0x1ac00000, v142
	s_andn2_b64 vcc, exec, s[40:41]
	s_waitcnt lgkmcnt(1)
	buffer_store_dwordx4 v[138:141], v134, s[12:15], 0 offen sc1
	s_waitcnt lgkmcnt(0)
	buffer_store_dwordx4 v[130:133], v134, s[12:15], 0 offen offset:1024 sc1
